# final tile loop with 8 row groups in flight (no norm change)
# baseline (speedup 1.0000x reference)
; __device__ __forceinline__ void phase_final(int vcu, int G) {
;     ...
;     for (unsigned i = (unsigned)vcu * NTHR + tid; i < n8; i += (unsigned)G * NTHR) {
;         const unsigned row = i >> 7, col = (i & 127) * 8;
;         const v4u d = *(const v4u*)(DL + (size_t)i * 8), e = *(const v4u*)(D0 + (size_t)row * DIN + d0_col((int)col));
;         f32x4 a = *(const f32x4*)(xin + (size_t)i * 8), b = *(const f32x4*)(xin + (size_t)i * 8 + 4);
;         a.x += bflo(d.x) + bflo(e.x); a.y += bfhi(d.x) + bfhi(e.x); a.z += bflo(d.y) + bflo(e.y); a.w += bfhi(d.y) + bfhi(e.y);
;         b.x += bflo(d.z) + bflo(e.z); b.y += bfhi(d.z) + bfhi(e.z); b.z += bflo(d.w) + bflo(e.w); b.w += bfhi(d.w) + bfhi(e.w);
;         *(f32x4*)(out + (size_t)i * 8) = a; *(f32x4*)(out + (size_t)i * 8 + 4) = b; }
.Lft_tile:
	s_mul_i32 s18, s17, s52
	s_add_u32 s18, s18, s16
	s_cmp_ge_u32 s18, 0x200
	s_cbranch_scc1 .Lft_done
	s_and_b32 s19, s18, 7
	s_lshr_b32 s18, s18, 3
	s_lshl_b32 s19, s19, 6
	s_add_u32 s18, s19, s18
	s_lshr_b32 s19, s18, 5
	s_lshl_b32 s19, s19, 3
	s_and_b32 s20, s18, 7
	s_add_u32 s19, s19, s20
	s_bfe_u32 s20, s18, 0x20003
	s_lshl_b32 s19, s19, 15
	s_lshl_b32 s20, s20, 5
	s_add_u32 s19, s19, s20
	v_lshrrev_b32_e32 v2, 5, v218
	v_lshlrev_b32_e32 v2, 7, v2
	v_and_b32_e32 v5, 31, v218
	v_add3_u32 v2, v2, v5, s19
	v_lshlrev_b32_e32 v0, 3, v2
	s_movk_i32 s22, 2
.Lft_loop:
	v_and_b32_e32 v14, 0x3f8, v0
	v_lshrrev_b32_e32 v5, 7, v2
	v_cmp_gt_u32_e32 vcc, s11, v14
	v_mul_u32_u24_e32 v10, 0xf00, v5
	v_mov_b32_e32 v11, v1
	v_cndmask_b32_e32 v5, v3, v4, vcc
	v_cmp_lt_u32_e32 vcc, s12, v14
	v_lshl_add_u64 v[6:7], v[0:1], 1, s[2:3]
	v_mov_b32_e32 v15, v1
	v_cndmask_b32_e32 v5, 0, v5, vcc
	v_lshlrev_b64 v[22:23], 2, v[0:1]
	v_lshl_add_u64 v[16:17], v[10:11], 1, s[6:7]
	v_add_lshl_u32 v14, v5, v14, 1
	global_load_dwordx4 v[32:35], v[6:7], off sc1
	v_lshl_add_u64 v[24:25], s[0:1], 0, v[22:23]
	v_lshl_add_u64 v[26:27], v[16:17], 0, v[14:15]
	global_load_dwordx4 v[36:39], v[24:25], off
	global_load_dwordx4 v[40:43], v[26:27], off
	global_load_dwordx4 v[44:47], v[24:25], off offset:16
	v_lshl_add_u64 v[48:49], s[4:5], 0, v[22:23]
	v_add_u32_e32 v2, 0x800, v2
	v_add_u32_e32 v0, 0x4000, v0
	v_and_b32_e32 v14, 0x3f8, v0
	v_lshrrev_b32_e32 v5, 7, v2
	v_cmp_gt_u32_e32 vcc, s11, v14
	v_mul_u32_u24_e32 v10, 0xf00, v5
	v_mov_b32_e32 v11, v1
	v_cndmask_b32_e32 v5, v3, v4, vcc
	v_cmp_lt_u32_e32 vcc, s12, v14
	v_lshl_add_u64 v[6:7], v[0:1], 1, s[2:3]
	v_mov_b32_e32 v15, v1
	v_cndmask_b32_e32 v5, 0, v5, vcc
	v_lshlrev_b64 v[22:23], 2, v[0:1]
	v_lshl_add_u64 v[16:17], v[10:11], 1, s[6:7]
	v_add_lshl_u32 v14, v5, v14, 1
	global_load_dwordx4 v[52:55], v[6:7], off sc1
	v_lshl_add_u64 v[24:25], s[0:1], 0, v[22:23]
	v_lshl_add_u64 v[26:27], v[16:17], 0, v[14:15]
	global_load_dwordx4 v[56:59], v[24:25], off
	global_load_dwordx4 v[60:63], v[26:27], off
	global_load_dwordx4 v[64:67], v[24:25], off offset:16
	v_lshl_add_u64 v[68:69], s[4:5], 0, v[22:23]
	v_add_u32_e32 v2, 0x800, v2
	v_add_u32_e32 v0, 0x4000, v0
	v_and_b32_e32 v14, 0x3f8, v0
	v_lshrrev_b32_e32 v5, 7, v2
	v_cmp_gt_u32_e32 vcc, s11, v14
	v_mul_u32_u24_e32 v10, 0xf00, v5
	v_mov_b32_e32 v11, v1
	v_cndmask_b32_e32 v5, v3, v4, vcc
	v_cmp_lt_u32_e32 vcc, s12, v14
	v_lshl_add_u64 v[6:7], v[0:1], 1, s[2:3]
	v_mov_b32_e32 v15, v1
	v_cndmask_b32_e32 v5, 0, v5, vcc
	v_lshlrev_b64 v[22:23], 2, v[0:1]
	v_lshl_add_u64 v[16:17], v[10:11], 1, s[6:7]
	v_add_lshl_u32 v14, v5, v14, 1
	global_load_dwordx4 v[72:75], v[6:7], off sc1
	v_lshl_add_u64 v[24:25], s[0:1], 0, v[22:23]
	v_lshl_add_u64 v[26:27], v[16:17], 0, v[14:15]
	global_load_dwordx4 v[76:79], v[24:25], off
	global_load_dwordx4 v[80:83], v[26:27], off
	global_load_dwordx4 v[84:87], v[24:25], off offset:16
	v_lshl_add_u64 v[88:89], s[4:5], 0, v[22:23]
	v_add_u32_e32 v2, 0x800, v2
	v_add_u32_e32 v0, 0x4000, v0
	v_and_b32_e32 v14, 0x3f8, v0
	v_lshrrev_b32_e32 v5, 7, v2
	v_cmp_gt_u32_e32 vcc, s11, v14
	v_mul_u32_u24_e32 v10, 0xf00, v5
	v_mov_b32_e32 v11, v1
	v_cndmask_b32_e32 v5, v3, v4, vcc
	v_cmp_lt_u32_e32 vcc, s12, v14
	v_lshl_add_u64 v[6:7], v[0:1], 1, s[2:3]
	v_mov_b32_e32 v15, v1
	v_cndmask_b32_e32 v5, 0, v5, vcc
	v_lshlrev_b64 v[22:23], 2, v[0:1]
	v_lshl_add_u64 v[16:17], v[10:11], 1, s[6:7]
	v_add_lshl_u32 v14, v5, v14, 1
	global_load_dwordx4 v[92:95], v[6:7], off sc1
	v_lshl_add_u64 v[24:25], s[0:1], 0, v[22:23]
	v_lshl_add_u64 v[26:27], v[16:17], 0, v[14:15]
	global_load_dwordx4 v[96:99], v[24:25], off
	global_load_dwordx4 v[100:103], v[26:27], off
	global_load_dwordx4 v[104:107], v[24:25], off offset:16
	v_lshl_add_u64 v[108:109], s[4:5], 0, v[22:23]
	v_add_u32_e32 v2, 0x800, v2
	v_add_u32_e32 v0, 0x4000, v0
	v_and_b32_e32 v14, 0x3f8, v0
	v_lshrrev_b32_e32 v5, 7, v2
	v_cmp_gt_u32_e32 vcc, s11, v14
	v_mul_u32_u24_e32 v10, 0xf00, v5
	v_mov_b32_e32 v11, v1
	v_cndmask_b32_e32 v5, v3, v4, vcc
	v_cmp_lt_u32_e32 vcc, s12, v14
	v_lshl_add_u64 v[6:7], v[0:1], 1, s[2:3]
	v_mov_b32_e32 v15, v1
	v_cndmask_b32_e32 v5, 0, v5, vcc
	v_lshlrev_b64 v[22:23], 2, v[0:1]
	v_lshl_add_u64 v[16:17], v[10:11], 1, s[6:7]
	v_add_lshl_u32 v14, v5, v14, 1
	global_load_dwordx4 v[112:115], v[6:7], off sc1
	v_lshl_add_u64 v[24:25], s[0:1], 0, v[22:23]
	v_lshl_add_u64 v[26:27], v[16:17], 0, v[14:15]
	global_load_dwordx4 v[116:119], v[24:25], off
	global_load_dwordx4 v[120:123], v[26:27], off
	global_load_dwordx4 v[124:127], v[24:25], off offset:16
	v_lshl_add_u64 v[128:129], s[4:5], 0, v[22:23]
	v_add_u32_e32 v2, 0x800, v2
	v_add_u32_e32 v0, 0x4000, v0
	v_and_b32_e32 v14, 0x3f8, v0
	v_lshrrev_b32_e32 v5, 7, v2
	v_cmp_gt_u32_e32 vcc, s11, v14
	v_mul_u32_u24_e32 v10, 0xf00, v5
	v_mov_b32_e32 v11, v1
	v_cndmask_b32_e32 v5, v3, v4, vcc
	v_cmp_lt_u32_e32 vcc, s12, v14
	v_lshl_add_u64 v[6:7], v[0:1], 1, s[2:3]
	v_mov_b32_e32 v15, v1
	v_cndmask_b32_e32 v5, 0, v5, vcc
	v_lshlrev_b64 v[22:23], 2, v[0:1]
	v_lshl_add_u64 v[16:17], v[10:11], 1, s[6:7]
	v_add_lshl_u32 v14, v5, v14, 1
	global_load_dwordx4 v[132:135], v[6:7], off sc1
	v_lshl_add_u64 v[24:25], s[0:1], 0, v[22:23]
	v_lshl_add_u64 v[26:27], v[16:17], 0, v[14:15]
	global_load_dwordx4 v[136:139], v[24:25], off
	global_load_dwordx4 v[140:143], v[26:27], off
	global_load_dwordx4 v[144:147], v[24:25], off offset:16
	v_lshl_add_u64 v[148:149], s[4:5], 0, v[22:23]
	v_add_u32_e32 v2, 0x800, v2
	v_add_u32_e32 v0, 0x4000, v0
	v_and_b32_e32 v14, 0x3f8, v0
	v_lshrrev_b32_e32 v5, 7, v2
	v_cmp_gt_u32_e32 vcc, s11, v14
	v_mul_u32_u24_e32 v10, 0xf00, v5
; __device__ __forceinline__ void phase_final(int vcu, int G) {
;     ...
;     for (unsigned i = (unsigned)vcu * NTHR + tid; i < n8; i += (unsigned)G * NTHR) {
;         const unsigned row = i >> 7, col = (i & 127) * 8;
;         const v4u d = *(const v4u*)(DL + (size_t)i * 8), e = *(const v4u*)(D0 + (size_t)row * DIN + d0_col((int)col));
;         f32x4 a = *(const f32x4*)(xin + (size_t)i * 8), b = *(const f32x4*)(xin + (size_t)i * 8 + 4);
;         a.x += bflo(d.x) + bflo(e.x); a.y += bfhi(d.x) + bfhi(e.x); a.z += bflo(d.y) + bflo(e.y); a.w += bfhi(d.y) + bfhi(e.y);
;         b.x += bflo(d.z) + bflo(e.z); b.y += bfhi(d.z) + bfhi(e.z); b.z += bflo(d.w) + bflo(e.w); b.w += bfhi(d.w) + bfhi(e.w);
;         *(f32x4*)(out + (size_t)i * 8) = a; *(f32x4*)(out + (size_t)i * 8 + 4) = b; }
	v_mov_b32_e32 v11, v1
	v_cndmask_b32_e32 v5, v3, v4, vcc
	v_cmp_lt_u32_e32 vcc, s12, v14
	v_lshl_add_u64 v[6:7], v[0:1], 1, s[2:3]
	v_mov_b32_e32 v15, v1
	v_cndmask_b32_e32 v5, 0, v5, vcc
	v_lshlrev_b64 v[22:23], 2, v[0:1]
	v_lshl_add_u64 v[16:17], v[10:11], 1, s[6:7]
	v_add_lshl_u32 v14, v5, v14, 1
	global_load_dwordx4 v[152:155], v[6:7], off sc1
	v_lshl_add_u64 v[24:25], s[0:1], 0, v[22:23]
	v_lshl_add_u64 v[26:27], v[16:17], 0, v[14:15]
	global_load_dwordx4 v[156:159], v[24:25], off
	global_load_dwordx4 v[160:163], v[26:27], off
	global_load_dwordx4 v[164:167], v[24:25], off offset:16
	v_lshl_add_u64 v[168:169], s[4:5], 0, v[22:23]
	v_add_u32_e32 v2, 0x800, v2
	v_add_u32_e32 v0, 0x4000, v0
	v_and_b32_e32 v14, 0x3f8, v0
	v_lshrrev_b32_e32 v5, 7, v2
	v_cmp_gt_u32_e32 vcc, s11, v14
	v_mul_u32_u24_e32 v10, 0xf00, v5
	v_mov_b32_e32 v11, v1
	v_cndmask_b32_e32 v5, v3, v4, vcc
	v_cmp_lt_u32_e32 vcc, s12, v14
	v_lshl_add_u64 v[6:7], v[0:1], 1, s[2:3]
	v_mov_b32_e32 v15, v1
	v_cndmask_b32_e32 v5, 0, v5, vcc
	v_lshlrev_b64 v[22:23], 2, v[0:1]
	v_lshl_add_u64 v[16:17], v[10:11], 1, s[6:7]
	v_add_lshl_u32 v14, v5, v14, 1
	global_load_dwordx4 v[172:175], v[6:7], off sc1
	v_lshl_add_u64 v[24:25], s[0:1], 0, v[22:23]
	v_lshl_add_u64 v[26:27], v[16:17], 0, v[14:15]
	global_load_dwordx4 v[176:179], v[24:25], off
	global_load_dwordx4 v[180:183], v[26:27], off
	global_load_dwordx4 v[184:187], v[24:25], off offset:16
	v_lshl_add_u64 v[188:189], s[4:5], 0, v[22:23]
	v_add_u32_e32 v2, 0x800, v2
	v_add_u32_e32 v0, 0x4000, v0
	s_waitcnt vmcnt(28)
	v_mov_b64_e32 v[22:23], v[48:49]
	v_mov_b64_e32 v[14:15], v[40:41]
	v_mov_b64_e32 v[16:17], v[42:43]
	v_mov_b64_e32 v[18:19], v[44:45]
	v_mov_b64_e32 v[20:21], v[46:47]
	v_mov_b64_e32 v[6:7], v[32:33]
	v_mov_b64_e32 v[8:9], v[34:35]
	v_mov_b64_e32 v[10:11], v[36:37]
	v_mov_b64_e32 v[12:13], v[38:39]
	v_lshlrev_b32_e32 v24, 16, v6
	v_and_b32_e32 v25, 0xffff0000, v6
	v_lshlrev_b32_e32 v6, 16, v7
	v_and_b32_e32 v7, 0xffff0000, v7
	v_lshlrev_b32_e32 v28, 16, v14
	v_and_b32_e32 v29, 0xffff0000, v14
	v_lshlrev_b32_e32 v14, 16, v15
	v_and_b32_e32 v15, 0xffff0000, v15
	v_lshlrev_b32_e32 v26, 16, v8
	v_and_b32_e32 v27, 0xffff0000, v8
	v_lshlrev_b32_e32 v8, 16, v9
	v_and_b32_e32 v9, 0xffff0000, v9
	v_lshlrev_b32_e32 v30, 16, v16
	v_and_b32_e32 v31, 0xffff0000, v16
	v_lshlrev_b32_e32 v16, 16, v17
	v_and_b32_e32 v17, 0xffff0000, v17
	v_pk_add_f32 v[24:25], v[24:25], v[28:29]
	v_pk_add_f32 v[14:15], v[6:7], v[14:15]
	v_pk_add_f32 v[26:27], v[26:27], v[30:31]
	v_pk_add_f32 v[16:17], v[8:9], v[16:17]
	v_pk_add_f32 v[6:7], v[10:11], v[24:25]
	v_pk_add_f32 v[8:9], v[12:13], v[14:15]
	v_pk_add_f32 v[10:11], v[18:19], v[26:27]
	v_pk_add_f32 v[12:13], v[20:21], v[16:17]
	global_store_dwordx4 v[22:23], v[6:9], off
	global_store_dwordx4 v[22:23], v[10:13], off offset:16
	s_waitcnt vmcnt(26)
	v_mov_b64_e32 v[22:23], v[68:69]
	v_mov_b64_e32 v[14:15], v[60:61]
	v_mov_b64_e32 v[16:17], v[62:63]
	v_mov_b64_e32 v[18:19], v[64:65]
	v_mov_b64_e32 v[20:21], v[66:67]
	v_mov_b64_e32 v[6:7], v[52:53]
	v_mov_b64_e32 v[8:9], v[54:55]
	v_mov_b64_e32 v[10:11], v[56:57]
	v_mov_b64_e32 v[12:13], v[58:59]
	v_lshlrev_b32_e32 v24, 16, v6
	v_and_b32_e32 v25, 0xffff0000, v6
	v_lshlrev_b32_e32 v6, 16, v7
	v_and_b32_e32 v7, 0xffff0000, v7
	v_lshlrev_b32_e32 v28, 16, v14
	v_and_b32_e32 v29, 0xffff0000, v14
	v_lshlrev_b32_e32 v14, 16, v15
	v_and_b32_e32 v15, 0xffff0000, v15
	v_lshlrev_b32_e32 v26, 16, v8
	v_and_b32_e32 v27, 0xffff0000, v8
	v_lshlrev_b32_e32 v8, 16, v9
	v_and_b32_e32 v9, 0xffff0000, v9
	v_lshlrev_b32_e32 v30, 16, v16
	v_and_b32_e32 v31, 0xffff0000, v16
	v_lshlrev_b32_e32 v16, 16, v17
	v_and_b32_e32 v17, 0xffff0000, v17
	v_pk_add_f32 v[24:25], v[24:25], v[28:29]
	v_pk_add_f32 v[14:15], v[6:7], v[14:15]
	v_pk_add_f32 v[26:27], v[26:27], v[30:31]
	v_pk_add_f32 v[16:17], v[8:9], v[16:17]
	v_pk_add_f32 v[6:7], v[10:11], v[24:25]
	v_pk_add_f32 v[8:9], v[12:13], v[14:15]
	v_pk_add_f32 v[10:11], v[18:19], v[26:27]
	v_pk_add_f32 v[12:13], v[20:21], v[16:17]
	global_store_dwordx4 v[22:23], v[6:9], off
	global_store_dwordx4 v[22:23], v[10:13], off offset:16
	s_waitcnt vmcnt(24)
	v_mov_b64_e32 v[22:23], v[88:89]
	v_mov_b64_e32 v[14:15], v[80:81]
	v_mov_b64_e32 v[16:17], v[82:83]
	v_mov_b64_e32 v[18:19], v[84:85]
	v_mov_b64_e32 v[20:21], v[86:87]
	v_mov_b64_e32 v[6:7], v[72:73]
	v_mov_b64_e32 v[8:9], v[74:75]
	v_mov_b64_e32 v[10:11], v[76:77]
	v_mov_b64_e32 v[12:13], v[78:79]
	v_lshlrev_b32_e32 v24, 16, v6
	v_and_b32_e32 v25, 0xffff0000, v6
	v_lshlrev_b32_e32 v6, 16, v7
	v_and_b32_e32 v7, 0xffff0000, v7
	v_lshlrev_b32_e32 v28, 16, v14
	v_and_b32_e32 v29, 0xffff0000, v14
	v_lshlrev_b32_e32 v14, 16, v15
	v_and_b32_e32 v15, 0xffff0000, v15
	v_lshlrev_b32_e32 v26, 16, v8
	v_and_b32_e32 v27, 0xffff0000, v8
	v_lshlrev_b32_e32 v8, 16, v9
	v_and_b32_e32 v9, 0xffff0000, v9
	v_lshlrev_b32_e32 v30, 16, v16
	v_and_b32_e32 v31, 0xffff0000, v16
	v_lshlrev_b32_e32 v16, 16, v17
	v_and_b32_e32 v17, 0xffff0000, v17
	v_pk_add_f32 v[24:25], v[24:25], v[28:29]
	v_pk_add_f32 v[14:15], v[6:7], v[14:15]
	v_pk_add_f32 v[26:27], v[26:27], v[30:31]
	v_pk_add_f32 v[16:17], v[8:9], v[16:17]
	v_pk_add_f32 v[6:7], v[10:11], v[24:25]
	v_pk_add_f32 v[8:9], v[12:13], v[14:15]
	v_pk_add_f32 v[10:11], v[18:19], v[26:27]
	v_pk_add_f32 v[12:13], v[20:21], v[16:17]
	global_store_dwordx4 v[22:23], v[6:9], off
	global_store_dwordx4 v[22:23], v[10:13], off offset:16
	s_waitcnt vmcnt(22)
; __device__ __forceinline__ void phase_final(int vcu, int G) {
;     ...
;     for (unsigned i = (unsigned)vcu * NTHR + tid; i < n8; i += (unsigned)G * NTHR) {
;         const unsigned row = i >> 7, col = (i & 127) * 8;
;         const v4u d = *(const v4u*)(DL + (size_t)i * 8), e = *(const v4u*)(D0 + (size_t)row * DIN + d0_col((int)col));
;         f32x4 a = *(const f32x4*)(xin + (size_t)i * 8), b = *(const f32x4*)(xin + (size_t)i * 8 + 4);
;         a.x += bflo(d.x) + bflo(e.x); a.y += bfhi(d.x) + bfhi(e.x); a.z += bflo(d.y) + bflo(e.y); a.w += bfhi(d.y) + bfhi(e.y);
;         b.x += bflo(d.z) + bflo(e.z); b.y += bfhi(d.z) + bfhi(e.z); b.z += bflo(d.w) + bflo(e.w); b.w += bfhi(d.w) + bfhi(e.w);
;         *(f32x4*)(out + (size_t)i * 8) = a; *(f32x4*)(out + (size_t)i * 8 + 4) = b; }
	v_mov_b64_e32 v[22:23], v[108:109]
	v_mov_b64_e32 v[14:15], v[100:101]
	v_mov_b64_e32 v[16:17], v[102:103]
	v_mov_b64_e32 v[18:19], v[104:105]
	v_mov_b64_e32 v[20:21], v[106:107]
	v_mov_b64_e32 v[6:7], v[92:93]
	v_mov_b64_e32 v[8:9], v[94:95]
	v_mov_b64_e32 v[10:11], v[96:97]
	v_mov_b64_e32 v[12:13], v[98:99]
	v_lshlrev_b32_e32 v24, 16, v6
	v_and_b32_e32 v25, 0xffff0000, v6
	v_lshlrev_b32_e32 v6, 16, v7
	v_and_b32_e32 v7, 0xffff0000, v7
	v_lshlrev_b32_e32 v28, 16, v14
	v_and_b32_e32 v29, 0xffff0000, v14
	v_lshlrev_b32_e32 v14, 16, v15
	v_and_b32_e32 v15, 0xffff0000, v15
	v_lshlrev_b32_e32 v26, 16, v8
	v_and_b32_e32 v27, 0xffff0000, v8
	v_lshlrev_b32_e32 v8, 16, v9
	v_and_b32_e32 v9, 0xffff0000, v9
	v_lshlrev_b32_e32 v30, 16, v16
	v_and_b32_e32 v31, 0xffff0000, v16
	v_lshlrev_b32_e32 v16, 16, v17
	v_and_b32_e32 v17, 0xffff0000, v17
	v_pk_add_f32 v[24:25], v[24:25], v[28:29]
	v_pk_add_f32 v[14:15], v[6:7], v[14:15]
	v_pk_add_f32 v[26:27], v[26:27], v[30:31]
	v_pk_add_f32 v[16:17], v[8:9], v[16:17]
	v_pk_add_f32 v[6:7], v[10:11], v[24:25]
	v_pk_add_f32 v[8:9], v[12:13], v[14:15]
	v_pk_add_f32 v[10:11], v[18:19], v[26:27]
	v_pk_add_f32 v[12:13], v[20:21], v[16:17]
	global_store_dwordx4 v[22:23], v[6:9], off
	global_store_dwordx4 v[22:23], v[10:13], off offset:16
	s_waitcnt vmcnt(20)
	v_mov_b64_e32 v[22:23], v[128:129]
	v_mov_b64_e32 v[14:15], v[120:121]
	v_mov_b64_e32 v[16:17], v[122:123]
	v_mov_b64_e32 v[18:19], v[124:125]
	v_mov_b64_e32 v[20:21], v[126:127]
	v_mov_b64_e32 v[6:7], v[112:113]
	v_mov_b64_e32 v[8:9], v[114:115]
	v_mov_b64_e32 v[10:11], v[116:117]
	v_mov_b64_e32 v[12:13], v[118:119]
	v_lshlrev_b32_e32 v24, 16, v6
	v_and_b32_e32 v25, 0xffff0000, v6
	v_lshlrev_b32_e32 v6, 16, v7
	v_and_b32_e32 v7, 0xffff0000, v7
	v_lshlrev_b32_e32 v28, 16, v14
	v_and_b32_e32 v29, 0xffff0000, v14
	v_lshlrev_b32_e32 v14, 16, v15
	v_and_b32_e32 v15, 0xffff0000, v15
	v_lshlrev_b32_e32 v26, 16, v8
	v_and_b32_e32 v27, 0xffff0000, v8
	v_lshlrev_b32_e32 v8, 16, v9
	v_and_b32_e32 v9, 0xffff0000, v9
	v_lshlrev_b32_e32 v30, 16, v16
	v_and_b32_e32 v31, 0xffff0000, v16
	v_lshlrev_b32_e32 v16, 16, v17
	v_and_b32_e32 v17, 0xffff0000, v17
	v_pk_add_f32 v[24:25], v[24:25], v[28:29]
	v_pk_add_f32 v[14:15], v[6:7], v[14:15]
	v_pk_add_f32 v[26:27], v[26:27], v[30:31]
	v_pk_add_f32 v[16:17], v[8:9], v[16:17]
	v_pk_add_f32 v[6:7], v[10:11], v[24:25]
	v_pk_add_f32 v[8:9], v[12:13], v[14:15]
	v_pk_add_f32 v[10:11], v[18:19], v[26:27]
	v_pk_add_f32 v[12:13], v[20:21], v[16:17]
	global_store_dwordx4 v[22:23], v[6:9], off
	global_store_dwordx4 v[22:23], v[10:13], off offset:16
	s_waitcnt vmcnt(18)
	v_mov_b64_e32 v[22:23], v[148:149]
	v_mov_b64_e32 v[14:15], v[140:141]
	v_mov_b64_e32 v[16:17], v[142:143]
	v_mov_b64_e32 v[18:19], v[144:145]
	v_mov_b64_e32 v[20:21], v[146:147]
	v_mov_b64_e32 v[6:7], v[132:133]
	v_mov_b64_e32 v[8:9], v[134:135]
	v_mov_b64_e32 v[10:11], v[136:137]
	v_mov_b64_e32 v[12:13], v[138:139]
	v_lshlrev_b32_e32 v24, 16, v6
	v_and_b32_e32 v25, 0xffff0000, v6
	v_lshlrev_b32_e32 v6, 16, v7
	v_and_b32_e32 v7, 0xffff0000, v7
	v_lshlrev_b32_e32 v28, 16, v14
	v_and_b32_e32 v29, 0xffff0000, v14
	v_lshlrev_b32_e32 v14, 16, v15
	v_and_b32_e32 v15, 0xffff0000, v15
	v_lshlrev_b32_e32 v26, 16, v8
	v_and_b32_e32 v27, 0xffff0000, v8
	v_lshlrev_b32_e32 v8, 16, v9
	v_and_b32_e32 v9, 0xffff0000, v9
	v_lshlrev_b32_e32 v30, 16, v16
	v_and_b32_e32 v31, 0xffff0000, v16
	v_lshlrev_b32_e32 v16, 16, v17
	v_and_b32_e32 v17, 0xffff0000, v17
	v_pk_add_f32 v[24:25], v[24:25], v[28:29]
	v_pk_add_f32 v[14:15], v[6:7], v[14:15]
	v_pk_add_f32 v[26:27], v[26:27], v[30:31]
	v_pk_add_f32 v[16:17], v[8:9], v[16:17]
	v_pk_add_f32 v[6:7], v[10:11], v[24:25]
	v_pk_add_f32 v[8:9], v[12:13], v[14:15]
	v_pk_add_f32 v[10:11], v[18:19], v[26:27]
	v_pk_add_f32 v[12:13], v[20:21], v[16:17]
	global_store_dwordx4 v[22:23], v[6:9], off
	global_store_dwordx4 v[22:23], v[10:13], off offset:16
	s_waitcnt vmcnt(16)
	v_mov_b64_e32 v[22:23], v[168:169]
	v_mov_b64_e32 v[14:15], v[160:161]
	v_mov_b64_e32 v[16:17], v[162:163]
	v_mov_b64_e32 v[18:19], v[164:165]
	v_mov_b64_e32 v[20:21], v[166:167]
	v_mov_b64_e32 v[6:7], v[152:153]
	v_mov_b64_e32 v[8:9], v[154:155]
	v_mov_b64_e32 v[10:11], v[156:157]
	v_mov_b64_e32 v[12:13], v[158:159]
	v_lshlrev_b32_e32 v24, 16, v6
	v_and_b32_e32 v25, 0xffff0000, v6
	v_lshlrev_b32_e32 v6, 16, v7
	v_and_b32_e32 v7, 0xffff0000, v7
	v_lshlrev_b32_e32 v28, 16, v14
	v_and_b32_e32 v29, 0xffff0000, v14
	v_lshlrev_b32_e32 v14, 16, v15
	v_and_b32_e32 v15, 0xffff0000, v15
	v_lshlrev_b32_e32 v26, 16, v8
	v_and_b32_e32 v27, 0xffff0000, v8
	v_lshlrev_b32_e32 v8, 16, v9
	v_and_b32_e32 v9, 0xffff0000, v9
	v_lshlrev_b32_e32 v30, 16, v16
	v_and_b32_e32 v31, 0xffff0000, v16
	v_lshlrev_b32_e32 v16, 16, v17
	v_and_b32_e32 v17, 0xffff0000, v17
	v_pk_add_f32 v[24:25], v[24:25], v[28:29]
	v_pk_add_f32 v[14:15], v[6:7], v[14:15]
	v_pk_add_f32 v[26:27], v[26:27], v[30:31]
	v_pk_add_f32 v[16:17], v[8:9], v[16:17]
	v_pk_add_f32 v[6:7], v[10:11], v[24:25]
	v_pk_add_f32 v[8:9], v[12:13], v[14:15]
	v_pk_add_f32 v[10:11], v[18:19], v[26:27]
	v_pk_add_f32 v[12:13], v[20:21], v[16:17]
	global_store_dwordx4 v[22:23], v[6:9], off
	global_store_dwordx4 v[22:23], v[10:13], off offset:16
	s_waitcnt vmcnt(14)
	v_mov_b64_e32 v[22:23], v[188:189]
	v_mov_b64_e32 v[14:15], v[180:181]
	v_mov_b64_e32 v[16:17], v[182:183]
	v_mov_b64_e32 v[18:19], v[184:185]
	v_mov_b64_e32 v[20:21], v[186:187]
	v_mov_b64_e32 v[6:7], v[172:173]
	v_mov_b64_e32 v[8:9], v[174:175]
	v_mov_b64_e32 v[10:11], v[176:177]
	v_mov_b64_e32 v[12:13], v[178:179]
	v_lshlrev_b32_e32 v24, 16, v6
	v_and_b32_e32 v25, 0xffff0000, v6
	v_lshlrev_b32_e32 v6, 16, v7
	v_and_b32_e32 v7, 0xffff0000, v7
	v_lshlrev_b32_e32 v28, 16, v14
	v_and_b32_e32 v29, 0xffff0000, v14
	v_lshlrev_b32_e32 v14, 16, v15
	v_and_b32_e32 v15, 0xffff0000, v15
	v_lshlrev_b32_e32 v26, 16, v8
	v_and_b32_e32 v27, 0xffff0000, v8
	v_lshlrev_b32_e32 v8, 16, v9
	v_and_b32_e32 v9, 0xffff0000, v9
	v_lshlrev_b32_e32 v30, 16, v16
	v_and_b32_e32 v31, 0xffff0000, v16
	v_lshlrev_b32_e32 v16, 16, v17
	v_and_b32_e32 v17, 0xffff0000, v17
	v_pk_add_f32 v[24:25], v[24:25], v[28:29]
	v_pk_add_f32 v[14:15], v[6:7], v[14:15]
	v_pk_add_f32 v[26:27], v[26:27], v[30:31]
	v_pk_add_f32 v[16:17], v[8:9], v[16:17]
	v_pk_add_f32 v[6:7], v[10:11], v[24:25]
	v_pk_add_f32 v[8:9], v[12:13], v[14:15]
	v_pk_add_f32 v[10:11], v[18:19], v[26:27]
	v_pk_add_f32 v[12:13], v[20:21], v[16:17]
	global_store_dwordx4 v[22:23], v[6:9], off
	global_store_dwordx4 v[22:23], v[10:13], off offset:16
	s_sub_u32 s22, s22, 1
	s_cmp_lg_u32 s22, 0
	s_cbranch_scc1 .Lft_loop
	s_add_u32 s17, s17, 1
	s_branch .Lft_tile
